# peel first K-loop iteration of the 4 main GEMM loops: first MFMA per accumulator takes C=0, per-unit zeroing of 127 acc regs removed
# speedup vs baseline: 1.0061x; 1.0053x over previous
.LBB0_118:
	s_add_u32 s58, s20, 0x100
	s_addc_u32 s59, s21, 0
	s_mov_b32 s66, -2
	s_add_u32 s20, s18, 0x100
	s_addc_u32 s21, s19, 0
	s_add_i32 s67, 0, 0x10000
	s_cmp_eq_u32 s66, 40
	s_cselect_b32 s25, s9, s21
	s_cselect_b32 s24, s8, s20
	s_cselect_b32 s23, s17, s59
	s_cselect_b32 s22, s16, s58
	s_add_i32 s70, 0, 0x14000
	v_add_u32_e32 v142, s67, v154
	v_add_u32_e32 v152, s70, v154
	ds_read_b128 v[130:133], v142
	ds_read_b128 v[134:137], v142 offset:1024
	ds_read_b128 v[138:141], v142 offset:2048
	ds_read_b128 v[142:145], v142 offset:3072
	ds_read_b128 v[156:159], v152
	ds_read_b128 v[160:163], v152 offset:1024
	ds_read_b128 v[164:167], v152 offset:2048
	ds_read_b128 v[168:171], v152 offset:3072
	v_lshl_add_u64 v[152:153], s[18:19], 0, v[148:149]
	s_add_i32 m0, s30, 0xc000
	ds_read_b128 v[172:175], v155
	ds_read_b128 v[176:179], v155 offset:1024
	ds_read_b128 v[180:183], v155 offset:2048
	ds_read_b128 v[184:187], v155 offset:3072
	ds_read_b128 v[192:195], v155 offset:4096
	ds_read_b128 v[196:199], v155 offset:5120
	ds_read_b128 v[200:203], v155 offset:6144
	ds_read_b128 v[204:207], v155 offset:7168
	global_load_lds_dwordx4 v[152:153], off
	v_lshl_add_u64 v[152:153], s[18:19], 0, v[150:151]
	s_add_i32 m0, s30, 0xe000
	s_nop 0
	global_load_lds_dwordx4 v[152:153], off
	s_waitcnt vmcnt(8)
	s_waitcnt lgkmcnt(0)
	s_barrier
	s_setprio 1
	s_waitcnt lgkmcnt(0)
	v_mfma_f32_16x16x32_bf16 v[126:129], v[130:133], v[172:175], 0
	v_mfma_f32_16x16x32_bf16 v[122:125], v[138:141], v[172:175], 0
	v_mfma_f32_16x16x32_bf16 v[118:121], v[130:133], v[180:183], 0
	v_mfma_f32_16x16x32_bf16 v[110:113], v[138:141], v[180:183], 0
	v_mfma_f32_16x16x32_bf16 v[94:97], v[130:133], v[192:195], 0
	v_mfma_f32_16x16x32_bf16 v[90:93], v[138:141], v[192:195], 0
	v_mfma_f32_16x16x32_bf16 v[86:89], v[130:133], v[200:203], 0
	v_mfma_f32_16x16x32_bf16 v[78:81], v[138:141], v[200:203], 0
	v_mfma_f32_16x16x32_bf16 v[126:129], v[134:137], v[176:179], v[126:129]
	v_mfma_f32_16x16x32_bf16 v[122:125], v[142:145], v[176:179], v[122:125]
	v_mfma_f32_16x16x32_bf16 v[118:121], v[134:137], v[184:187], v[118:121]
	v_mfma_f32_16x16x32_bf16 v[110:113], v[142:145], v[184:187], v[110:113]
	v_mfma_f32_16x16x32_bf16 v[94:97], v[134:137], v[196:199], v[94:97]
	v_mfma_f32_16x16x32_bf16 v[90:93], v[142:145], v[196:199], v[90:93]
	v_mfma_f32_16x16x32_bf16 v[86:89], v[134:137], v[204:207], v[86:89]
	v_mfma_f32_16x16x32_bf16 v[78:81], v[142:145], v[204:207], v[78:81]
	s_setprio 0
	s_setprio 1
	v_mfma_f32_16x16x32_bf16 v[114:117], v[156:159], v[172:175], 0
	v_mfma_f32_16x16x32_bf16 v[106:109], v[164:167], v[172:175], 0
	v_mfma_f32_16x16x32_bf16 v[102:105], v[156:159], v[180:183], 0
	v_mfma_f32_16x16x32_bf16 v[98:101], v[164:167], v[180:183], 0
	v_mfma_f32_16x16x32_bf16 v[82:85], v[156:159], v[192:195], 0
	v_mfma_f32_16x16x32_bf16 v[74:77], v[164:167], v[192:195], 0
	v_mfma_f32_16x16x32_bf16 v[70:73], v[156:159], v[200:203], 0
	v_mfma_f32_16x16x32_bf16 v[66:69], v[164:167], v[200:203], 0
	v_mfma_f32_16x16x32_bf16 v[114:117], v[160:163], v[176:179], v[114:117]
	v_mfma_f32_16x16x32_bf16 v[106:109], v[168:171], v[176:179], v[106:109]
	v_mfma_f32_16x16x32_bf16 v[102:105], v[160:163], v[184:187], v[102:105]
	v_mfma_f32_16x16x32_bf16 v[98:101], v[168:171], v[184:187], v[98:101]
	v_mfma_f32_16x16x32_bf16 v[82:85], v[160:163], v[196:199], v[82:85]
	v_mfma_f32_16x16x32_bf16 v[74:77], v[168:171], v[196:199], v[74:77]
	v_mfma_f32_16x16x32_bf16 v[70:73], v[160:163], v[204:207], v[70:73]
	v_mfma_f32_16x16x32_bf16 v[66:69], v[168:171], v[204:207], v[66:69]
	s_setprio 0
	s_barrier
	s_add_i32 s18, s67, s29
	v_lshl_add_u64 v[152:153], s[22:23], 0, v[0:1]
	s_mov_b32 m0, s18
	ds_read_b128 v[172:175], v155 offset:16384
	ds_read_b128 v[176:179], v155 offset:17408
	ds_read_b128 v[180:183], v155 offset:18432
	ds_read_b128 v[184:187], v155 offset:19456
	ds_read_b128 v[192:195], v155 offset:20480
	ds_read_b128 v[196:199], v155 offset:21504
	ds_read_b128 v[200:203], v155 offset:22528
	ds_read_b128 v[204:207], v155 offset:23552
	global_load_lds_dwordx4 v[152:153], off
	s_add_i32 m0, s18, 0x2000
	s_add_u32 s18, s22, 0xb0000
	v_lshl_add_u64 v[188:189], s[22:23], 0, v[146:147]
	s_addc_u32 s19, s23, 0
	s_add_i32 s67, s70, s29
	global_load_lds_dwordx4 v[188:189], off
	v_lshl_add_u64 v[208:209], s[18:19], 0, v[0:1]
	s_mov_b32 m0, s67
	v_lshl_add_u64 v[210:211], s[24:25], 0, v[146:147]
	global_load_lds_dwordx4 v[208:209], off
	v_lshl_add_u64 v[208:209], s[18:19], 0, v[146:147]
	s_add_i32 m0, s67, 0x2000
	s_nop 0
	global_load_lds_dwordx4 v[208:209], off
	v_lshl_add_u64 v[208:209], s[24:25], 0, v[0:1]
	s_mov_b32 m0, s30
	s_nop 0
	global_load_lds_dwordx4 v[208:209], off
	s_mov_b32 m0, s31
	s_nop 0
	global_load_lds_dwordx4 v[210:211], off
	s_waitcnt vmcnt(8)
	s_waitcnt lgkmcnt(0)
	s_barrier
	s_setprio 1
	s_waitcnt lgkmcnt(0)
	v_mfma_f32_16x16x32_bf16 v[62:65], v[130:133], v[172:175], 0
	v_mfma_f32_16x16x32_bf16 v[58:61], v[138:141], v[172:175], 0
	v_mfma_f32_16x16x32_bf16 v[54:57], v[130:133], v[180:183], 0
	v_mfma_f32_16x16x32_bf16 v[46:49], v[138:141], v[180:183], 0
	v_mfma_f32_16x16x32_bf16 v[30:33], v[130:133], v[192:195], 0
	v_mfma_f32_16x16x32_bf16 v[26:29], v[138:141], v[192:195], 0
	v_mfma_f32_16x16x32_bf16 v[22:25], v[130:133], v[200:203], 0
	v_mfma_f32_16x16x32_bf16 v[14:17], v[138:141], v[200:203], 0
	v_mfma_f32_16x16x32_bf16 v[62:65], v[134:137], v[176:179], v[62:65]
	v_mfma_f32_16x16x32_bf16 v[58:61], v[142:145], v[176:179], v[58:61]
	v_mfma_f32_16x16x32_bf16 v[54:57], v[134:137], v[184:187], v[54:57]
	v_mfma_f32_16x16x32_bf16 v[46:49], v[142:145], v[184:187], v[46:49]
	v_mfma_f32_16x16x32_bf16 v[30:33], v[134:137], v[196:199], v[30:33]
	v_mfma_f32_16x16x32_bf16 v[26:29], v[142:145], v[196:199], v[26:29]
	v_mfma_f32_16x16x32_bf16 v[22:25], v[134:137], v[204:207], v[22:25]
	v_mfma_f32_16x16x32_bf16 v[14:17], v[142:145], v[204:207], v[14:17]
	s_setprio 0
	s_setprio 1
	v_mfma_f32_16x16x32_bf16 v[50:53], v[156:159], v[172:175], 0
	v_mfma_f32_16x16x32_bf16 v[42:45], v[164:167], v[172:175], 0
	v_mfma_f32_16x16x32_bf16 v[38:41], v[156:159], v[180:183], 0
	v_mfma_f32_16x16x32_bf16 v[34:37], v[164:167], v[180:183], 0
	v_mfma_f32_16x16x32_bf16 v[18:21], v[156:159], v[192:195], 0
	v_mfma_f32_16x16x32_bf16 v[10:13], v[164:167], v[192:195], 0
	v_mfma_f32_16x16x32_bf16 v[6:9], v[156:159], v[200:203], 0
	v_mfma_f32_16x16x32_bf16 v[2:5], v[164:167], v[200:203], 0
	v_mfma_f32_16x16x32_bf16 v[50:53], v[160:163], v[176:179], v[50:53]
	v_mfma_f32_16x16x32_bf16 v[42:45], v[168:171], v[176:179], v[42:45]
	v_mfma_f32_16x16x32_bf16 v[38:41], v[160:163], v[184:187], v[38:41]
	v_mfma_f32_16x16x32_bf16 v[34:37], v[168:171], v[184:187], v[34:37]
	v_mfma_f32_16x16x32_bf16 v[18:21], v[160:163], v[196:199], v[18:21]
	v_mfma_f32_16x16x32_bf16 v[10:13], v[168:171], v[196:199], v[10:13]
	v_mfma_f32_16x16x32_bf16 v[6:9], v[160:163], v[204:207], v[6:9]
	v_mfma_f32_16x16x32_bf16 v[2:5], v[168:171], v[204:207], v[2:5]
	s_setprio 0
	s_barrier
	s_add_i32 s67, 0, 0x18000
	s_add_i32 s70, 0, 0x1c000
	v_add_u32_e32 v142, s67, v154
	v_add_u32_e32 v168, s70, v154
	ds_read_b128 v[130:133], v142
	ds_read_b128 v[134:137], v142 offset:1024
	ds_read_b128 v[138:141], v142 offset:2048
	ds_read_b128 v[142:145], v142 offset:3072
	ds_read_b128 v[156:159], v168
	ds_read_b128 v[160:163], v168 offset:1024
	ds_read_b128 v[164:167], v168 offset:2048
	ds_read_b128 v[168:171], v168 offset:3072
	s_add_u32 s18, s24, 0xb0000
	s_addc_u32 s19, s25, 0
	s_mov_b32 m0, s33
	v_lshl_add_u64 v[212:213], s[18:19], 0, v[0:1]
	ds_read_b128 v[172:175], v155 offset:32768
	ds_read_b128 v[176:179], v155 offset:33792
	ds_read_b128 v[180:183], v155 offset:34816
	ds_read_b128 v[184:187], v155 offset:35840
	ds_read_b128 v[192:195], v155 offset:36864
	ds_read_b128 v[196:199], v155 offset:37888
	ds_read_b128 v[200:203], v155 offset:38912
	ds_read_b128 v[204:207], v155 offset:39936
	global_load_lds_dwordx4 v[212:213], off
	v_lshl_add_u64 v[212:213], s[18:19], 0, v[146:147]
	s_mov_b32 m0, s38
	s_nop 0
	global_load_lds_dwordx4 v[212:213], off
	s_waitcnt vmcnt(8)
	s_waitcnt lgkmcnt(0)
	s_barrier
	s_setprio 1
	s_waitcnt lgkmcnt(0)
	v_mfma_f32_16x16x32_bf16 v[126:129], v[130:133], v[172:175], v[126:129]
	v_mfma_f32_16x16x32_bf16 v[122:125], v[138:141], v[172:175], v[122:125]
	v_mfma_f32_16x16x32_bf16 v[118:121], v[130:133], v[180:183], v[118:121]
	v_mfma_f32_16x16x32_bf16 v[110:113], v[138:141], v[180:183], v[110:113]
	v_mfma_f32_16x16x32_bf16 v[94:97], v[130:133], v[192:195], v[94:97]
	v_mfma_f32_16x16x32_bf16 v[90:93], v[138:141], v[192:195], v[90:93]
	v_mfma_f32_16x16x32_bf16 v[86:89], v[130:133], v[200:203], v[86:89]
	v_mfma_f32_16x16x32_bf16 v[78:81], v[138:141], v[200:203], v[78:81]
	v_mfma_f32_16x16x32_bf16 v[126:129], v[134:137], v[176:179], v[126:129]
	v_mfma_f32_16x16x32_bf16 v[122:125], v[142:145], v[176:179], v[122:125]
	v_mfma_f32_16x16x32_bf16 v[118:121], v[134:137], v[184:187], v[118:121]
	v_mfma_f32_16x16x32_bf16 v[110:113], v[142:145], v[184:187], v[110:113]
	v_mfma_f32_16x16x32_bf16 v[94:97], v[134:137], v[196:199], v[94:97]
	v_mfma_f32_16x16x32_bf16 v[90:93], v[142:145], v[196:199], v[90:93]
	v_mfma_f32_16x16x32_bf16 v[86:89], v[134:137], v[204:207], v[86:89]
	v_mfma_f32_16x16x32_bf16 v[78:81], v[142:145], v[204:207], v[78:81]
	s_setprio 0
	s_setprio 1
	v_mfma_f32_16x16x32_bf16 v[114:117], v[156:159], v[172:175], v[114:117]
	v_mfma_f32_16x16x32_bf16 v[106:109], v[164:167], v[172:175], v[106:109]
	v_mfma_f32_16x16x32_bf16 v[102:105], v[156:159], v[180:183], v[102:105]
	v_mfma_f32_16x16x32_bf16 v[98:101], v[164:167], v[180:183], v[98:101]
	v_mfma_f32_16x16x32_bf16 v[82:85], v[156:159], v[192:195], v[82:85]
	v_mfma_f32_16x16x32_bf16 v[74:77], v[164:167], v[192:195], v[74:77]
	v_mfma_f32_16x16x32_bf16 v[70:73], v[156:159], v[200:203], v[70:73]
	v_mfma_f32_16x16x32_bf16 v[66:69], v[164:167], v[200:203], v[66:69]
	v_mfma_f32_16x16x32_bf16 v[114:117], v[160:163], v[176:179], v[114:117]
	v_mfma_f32_16x16x32_bf16 v[106:109], v[168:171], v[176:179], v[106:109]
	v_mfma_f32_16x16x32_bf16 v[102:105], v[160:163], v[184:187], v[102:105]
	v_mfma_f32_16x16x32_bf16 v[98:101], v[168:171], v[184:187], v[98:101]
	v_mfma_f32_16x16x32_bf16 v[82:85], v[160:163], v[196:199], v[82:85]
	v_mfma_f32_16x16x32_bf16 v[74:77], v[168:171], v[196:199], v[74:77]
	v_mfma_f32_16x16x32_bf16 v[70:73], v[160:163], v[204:207], v[70:73]
	v_mfma_f32_16x16x32_bf16 v[66:69], v[168:171], v[204:207], v[66:69]
	s_setprio 0
	s_barrier
	s_add_i32 s18, s67, s29
	v_lshl_add_u64 v[152:153], v[152:153], 0, s[86:87]
	s_mov_b32 m0, s18
	ds_read_b128 v[172:175], v155 offset:49152
	ds_read_b128 v[176:179], v155 offset:50176
	ds_read_b128 v[180:183], v155 offset:51200
	ds_read_b128 v[184:187], v155 offset:52224
	ds_read_b128 v[192:195], v155 offset:53248
	ds_read_b128 v[196:199], v155 offset:54272
	ds_read_b128 v[200:203], v155 offset:55296
	ds_read_b128 v[204:207], v155 offset:56320
	global_load_lds_dwordx4 v[152:153], off
	s_add_i32 m0, s18, 0x2000
	s_add_u32 s18, s22, 0xb0080
	v_lshl_add_u64 v[152:153], v[188:189], 0, s[86:87]
	s_addc_u32 s19, s23, 0
	s_add_i32 s22, s70, s29
	global_load_lds_dwordx4 v[152:153], off
	v_lshl_add_u64 v[152:153], s[18:19], 0, v[0:1]
	s_mov_b32 m0, s22
	s_nop 0
	global_load_lds_dwordx4 v[152:153], off
	v_lshl_add_u64 v[152:153], s[18:19], 0, v[146:147]
	s_add_i32 m0, s22, 0x2000
	s_nop 0
	global_load_lds_dwordx4 v[152:153], off
	v_lshl_add_u64 v[152:153], v[208:209], 0, s[86:87]
	s_mov_b32 m0, s44
	s_nop 0
	global_load_lds_dwordx4 v[152:153], off
	v_lshl_add_u64 v[152:153], v[210:211], 0, s[86:87]
	s_mov_b32 m0, s45
	s_nop 0
	global_load_lds_dwordx4 v[152:153], off
	s_waitcnt vmcnt(8)
	s_waitcnt lgkmcnt(0)
	s_barrier
	s_setprio 1
	s_waitcnt lgkmcnt(0)
	v_mfma_f32_16x16x32_bf16 v[62:65], v[130:133], v[172:175], v[62:65]
	v_mfma_f32_16x16x32_bf16 v[58:61], v[138:141], v[172:175], v[58:61]
	v_mfma_f32_16x16x32_bf16 v[54:57], v[130:133], v[180:183], v[54:57]
	v_mfma_f32_16x16x32_bf16 v[46:49], v[138:141], v[180:183], v[46:49]
	v_mfma_f32_16x16x32_bf16 v[30:33], v[130:133], v[192:195], v[30:33]
	v_mfma_f32_16x16x32_bf16 v[26:29], v[138:141], v[192:195], v[26:29]
	v_mfma_f32_16x16x32_bf16 v[22:25], v[130:133], v[200:203], v[22:25]
	v_mfma_f32_16x16x32_bf16 v[14:17], v[138:141], v[200:203], v[14:17]
	v_mfma_f32_16x16x32_bf16 v[62:65], v[134:137], v[176:179], v[62:65]
	v_mfma_f32_16x16x32_bf16 v[58:61], v[142:145], v[176:179], v[58:61]
	v_mfma_f32_16x16x32_bf16 v[54:57], v[134:137], v[184:187], v[54:57]
	v_mfma_f32_16x16x32_bf16 v[46:49], v[142:145], v[184:187], v[46:49]
	v_mfma_f32_16x16x32_bf16 v[30:33], v[134:137], v[196:199], v[30:33]
	v_mfma_f32_16x16x32_bf16 v[26:29], v[142:145], v[196:199], v[26:29]
	v_mfma_f32_16x16x32_bf16 v[22:25], v[134:137], v[204:207], v[22:25]
	v_mfma_f32_16x16x32_bf16 v[14:17], v[142:145], v[204:207], v[14:17]
	s_setprio 0
	s_setprio 1
	v_mfma_f32_16x16x32_bf16 v[50:53], v[156:159], v[172:175], v[50:53]
	v_mfma_f32_16x16x32_bf16 v[42:45], v[164:167], v[172:175], v[42:45]
	v_mfma_f32_16x16x32_bf16 v[38:41], v[156:159], v[180:183], v[38:41]
	v_mfma_f32_16x16x32_bf16 v[34:37], v[164:167], v[180:183], v[34:37]
	v_mfma_f32_16x16x32_bf16 v[18:21], v[156:159], v[192:195], v[18:21]
	v_mfma_f32_16x16x32_bf16 v[10:13], v[164:167], v[192:195], v[10:13]
	v_mfma_f32_16x16x32_bf16 v[6:9], v[156:159], v[200:203], v[6:9]
	v_mfma_f32_16x16x32_bf16 v[2:5], v[164:167], v[200:203], v[2:5]
	v_mfma_f32_16x16x32_bf16 v[50:53], v[160:163], v[176:179], v[50:53]
	v_mfma_f32_16x16x32_bf16 v[42:45], v[168:171], v[176:179], v[42:45]
	v_mfma_f32_16x16x32_bf16 v[38:41], v[160:163], v[184:187], v[38:41]
	v_mfma_f32_16x16x32_bf16 v[34:37], v[168:171], v[184:187], v[34:37]
	v_mfma_f32_16x16x32_bf16 v[18:21], v[160:163], v[196:199], v[18:21]
	v_mfma_f32_16x16x32_bf16 v[10:13], v[168:171], v[196:199], v[10:13]
	v_mfma_f32_16x16x32_bf16 v[6:9], v[160:163], v[204:207], v[6:9]
	v_mfma_f32_16x16x32_bf16 v[2:5], v[168:171], v[204:207], v[2:5]
	s_setprio 0
	s_barrier
	s_add_i32 s66, s66, 2
	s_add_u32 s58, s58, 0x100
	s_addc_u32 s59, s59, 0
	s_cmp_gt_u32 s66, 41
	s_mov_b64 s[18:19], s[20:21]

.LBB0_159:
	s_and_b32 s67, s44, 3
	v_and_b32_e32 v17, 48, v16
	v_lshlrev_b32_e32 v18, 6, v16
	s_movk_i32 s44, 0x3c0
	s_add_i32 m0, s9, 0x18000
	v_lshl_add_u64 v[8:9], v[8:9], 0, s[86:87]
	s_lshl_b32 s70, s59, 6
	v_and_or_b32 v17, v18, s44, v17
	s_lshl_b32 s44, s59, 13
	s_lshl_b32 s59, s67, 12
	s_waitcnt vmcnt(2)
	s_barrier
	global_load_lds_dwordx4 v[8:9], off
	v_lshl_add_u64 v[6:7], v[6:7], 0, s[86:87]
	s_add_i32 m0, s9, 0x1a000
	s_add_i32 s71, s9, 0x8000
	s_add_i32 s74, s9, 0xa000
	global_load_lds_dwordx4 v[6:7], off
	v_lshl_add_u64 v[4:5], v[4:5], 0, s[86:87]
	s_mov_b32 m0, s71
	s_add_u32 s76, s6, 0x40080
	global_load_lds_dwordx4 v[4:5], off
	v_lshl_add_u64 v[2:3], v[2:3], 0, s[86:87]
	s_mov_b32 m0, s74
	s_addc_u32 s77, s7, 0
	global_load_lds_dwordx4 v[2:3], off
	s_add_i32 m0, s9, 0x1c000
	v_lshl_add_u64 v[2:3], s[76:77], 0, v[0:1]
	global_load_lds_dwordx4 v[2:3], off
	v_lshl_add_u64 v[2:3], s[76:77], 0, v[134:135]
	s_add_i32 m0, s9, 0x1e000
	v_lshlrev_b32_e32 v16, 2, v16
	global_load_lds_dwordx4 v[2:3], off
	s_waitcnt vmcnt(6)
	s_barrier
	s_load_dwordx2 s[76:77], s[0:1], 0xc8
	v_lshlrev_b32_e32 v2, 14, v10
	v_and_b32_e32 v2, 0xffff8000, v2
	v_and_b32_e32 v16, 32, v16
	v_lshl_add_u32 v2, v11, 11, v2
	s_waitcnt lgkmcnt(0)
	s_add_u32 s76, s76, s58
	s_addc_u32 s77, s77, s45
	v_and_b32_e32 v3, 1, v10
	v_bitop3_b32 v18, v17, s44, v16 bitop3:0xde
	v_lshl_or_b32 v2, v3, 6, v2
	s_add_u32 s44, s33, s58
	v_lshl_add_u32 v2, v12, 1, v2
	v_mov_b32_e32 v3, v1
	s_addc_u32 s45, s42, s45
	v_lshl_add_u64 v[136:137], s[44:45], 0, v[2:3]
	v_lshlrev_b32_e32 v2, 14, v13
	v_and_b32_e32 v2, 0xffff8000, v2
	v_lshl_add_u32 v2, v14, 11, v2
	v_and_b32_e32 v3, 1, v13
	v_lshl_or_b32 v2, v3, 6, v2
	v_lshl_add_u32 v2, v15, 1, v2
	v_mov_b32_e32 v3, v1
	v_lshl_add_u64 v[138:139], s[44:45], 0, v[2:3]
	s_add_u32 s78, s43, s38
	v_bitop3_b32 v140, v17, s59, v16 bitop3:0xde
	s_addc_u32 s79, s46, s39
	s_mov_b32 s81, -2
	s_mov_b64 s[38:39], 0
	v_add_u32_e32 v141, 0, v18
	s_add_u32 s44, s76, s38
	s_addc_u32 s45, s77, s39
	s_add_u32 s44, s44, 0x3800900
	s_addc_u32 s45, s45, 0
	s_add_u32 s85, s78, s38
	s_addc_u32 s93, s79, s39
	s_add_i32 vcc_lo, 0, 0x10000
	s_cmpk_eq_i32 s38, 0x700
	s_cselect_b32 s59, s29, s45
	s_cselect_b32 s58, s28, s44
	s_cselect_b32 s45, s7, s93
	s_cselect_b32 s44, s6, s85
	s_add_i32 s85, 0, 0x14000
	v_add_u32_e32 v154, vcc_lo, v140
	v_add_u32_e32 v170, s85, v140
	ds_read_b128 v[142:145], v154
	ds_read_b128 v[146:149], v154 offset:1024
	ds_read_b128 v[150:153], v154 offset:2048
	ds_read_b128 v[154:157], v154 offset:3072
	ds_read_b128 v[158:161], v170
	ds_read_b128 v[162:165], v170 offset:1024
	ds_read_b128 v[166:169], v170 offset:2048
	ds_read_b128 v[170:173], v170 offset:3072
	v_lshl_add_u64 v[208:209], v[136:137], 0, s[38:39]
	s_add_i32 m0, s9, 0xc000
	ds_read_b128 v[174:177], v141
	ds_read_b128 v[178:181], v141 offset:1024
	ds_read_b128 v[182:185], v141 offset:2048
	ds_read_b128 v[186:189], v141 offset:3072
	ds_read_b128 v[192:195], v141 offset:4096
	ds_read_b128 v[196:199], v141 offset:5120
	ds_read_b128 v[200:203], v141 offset:6144
	ds_read_b128 v[204:207], v141 offset:7168
	global_load_lds_dwordx4 v[208:209], off
	v_lshl_add_u64 v[208:209], v[138:139], 0, s[38:39]
	s_add_i32 m0, s9, 0xe000
	s_nop 0
	global_load_lds_dwordx4 v[208:209], off
	s_waitcnt vmcnt(8)
	s_waitcnt lgkmcnt(0)
	s_barrier
	s_setprio 1
	s_waitcnt lgkmcnt(0)
	v_mfma_f32_16x16x32_bf16 v[126:129], v[142:145], v[174:177], 0
	v_mfma_f32_16x16x32_bf16 v[122:125], v[150:153], v[174:177], 0
	v_mfma_f32_16x16x32_bf16 v[118:121], v[142:145], v[182:185], 0
	v_mfma_f32_16x16x32_bf16 v[114:117], v[150:153], v[182:185], 0
	v_mfma_f32_16x16x32_bf16 v[102:105], v[142:145], v[192:195], 0
	v_mfma_f32_16x16x32_bf16 v[98:101], v[150:153], v[192:195], 0
	v_mfma_f32_16x16x32_bf16 v[86:89], v[142:145], v[200:203], 0
	v_mfma_f32_16x16x32_bf16 v[82:85], v[150:153], v[200:203], 0
	v_mfma_f32_16x16x32_bf16 v[126:129], v[146:149], v[178:181], v[126:129]
	v_mfma_f32_16x16x32_bf16 v[122:125], v[154:157], v[178:181], v[122:125]
	v_mfma_f32_16x16x32_bf16 v[118:121], v[146:149], v[186:189], v[118:121]
	v_mfma_f32_16x16x32_bf16 v[114:117], v[154:157], v[186:189], v[114:117]
	v_mfma_f32_16x16x32_bf16 v[102:105], v[146:149], v[196:199], v[102:105]
	v_mfma_f32_16x16x32_bf16 v[98:101], v[154:157], v[196:199], v[98:101]
	v_mfma_f32_16x16x32_bf16 v[86:89], v[146:149], v[204:207], v[86:89]
	v_mfma_f32_16x16x32_bf16 v[82:85], v[154:157], v[204:207], v[82:85]
	s_setprio 0
	s_setprio 1
	v_mfma_f32_16x16x32_bf16 v[110:113], v[158:161], v[174:177], 0
	v_mfma_f32_16x16x32_bf16 v[106:109], v[166:169], v[174:177], 0
	v_mfma_f32_16x16x32_bf16 v[94:97], v[158:161], v[182:185], 0
	v_mfma_f32_16x16x32_bf16 v[90:93], v[166:169], v[182:185], 0
	v_mfma_f32_16x16x32_bf16 v[78:81], v[158:161], v[192:195], 0
	v_mfma_f32_16x16x32_bf16 v[74:77], v[166:169], v[192:195], 0
	v_mfma_f32_16x16x32_bf16 v[70:73], v[158:161], v[200:203], 0
	v_mfma_f32_16x16x32_bf16 v[66:69], v[166:169], v[200:203], 0
	v_mfma_f32_16x16x32_bf16 v[110:113], v[162:165], v[178:181], v[110:113]
	v_mfma_f32_16x16x32_bf16 v[106:109], v[170:173], v[178:181], v[106:109]
	v_mfma_f32_16x16x32_bf16 v[94:97], v[162:165], v[186:189], v[94:97]
	v_mfma_f32_16x16x32_bf16 v[90:93], v[170:173], v[186:189], v[90:93]
	v_mfma_f32_16x16x32_bf16 v[78:81], v[162:165], v[196:199], v[78:81]
	v_mfma_f32_16x16x32_bf16 v[74:77], v[170:173], v[196:199], v[74:77]
	v_mfma_f32_16x16x32_bf16 v[70:73], v[162:165], v[204:207], v[70:73]
	v_mfma_f32_16x16x32_bf16 v[66:69], v[170:173], v[204:207], v[66:69]
	s_setprio 0
	s_barrier
	s_add_i32 s93, vcc_lo, s49
	v_lshl_add_u64 v[208:209], s[44:45], 0, v[0:1]
	s_mov_b32 m0, s93
	ds_read_b128 v[174:177], v141 offset:16384
	ds_read_b128 v[178:181], v141 offset:17408
	ds_read_b128 v[182:185], v141 offset:18432
	ds_read_b128 v[186:189], v141 offset:19456
	ds_read_b128 v[192:195], v141 offset:20480
	ds_read_b128 v[196:199], v141 offset:21504
	ds_read_b128 v[200:203], v141 offset:22528
	ds_read_b128 v[204:207], v141 offset:23552
	global_load_lds_dwordx4 v[208:209], off
	s_add_i32 m0, s93, 0x2000
	s_add_u32 vcc_lo, s44, 0x40000
	v_lshl_add_u64 v[210:211], s[44:45], 0, v[134:135]
	s_addc_u32 vcc_hi, s45, 0
	s_add_i32 s85, s85, s49
	global_load_lds_dwordx4 v[210:211], off
	v_lshl_add_u64 v[212:213], vcc, 0, v[0:1]
	s_mov_b32 m0, s85
	v_lshl_add_u64 v[214:215], s[58:59], 0, v[132:133]
	global_load_lds_dwordx4 v[212:213], off
	v_lshl_add_u64 v[212:213], vcc, 0, v[134:135]
	s_add_i32 m0, s85, 0x2000
	s_nop 0
	global_load_lds_dwordx4 v[212:213], off
	v_lshl_add_u64 v[212:213], s[58:59], 0, v[130:131]
	s_mov_b32 m0, s9
	s_nop 0
	global_load_lds_dwordx4 v[212:213], off
	s_mov_b32 m0, s56
	s_nop 0
	global_load_lds_dwordx4 v[214:215], off
	s_waitcnt vmcnt(8)
	s_waitcnt lgkmcnt(0)
	s_barrier
	s_setprio 1
	s_waitcnt lgkmcnt(0)
	v_mfma_f32_16x16x32_bf16 v[62:65], v[142:145], v[174:177], 0
	v_mfma_f32_16x16x32_bf16 v[58:61], v[150:153], v[174:177], 0
	v_mfma_f32_16x16x32_bf16 v[54:57], v[142:145], v[182:185], 0
	v_mfma_f32_16x16x32_bf16 v[50:53], v[150:153], v[182:185], 0
	v_mfma_f32_16x16x32_bf16 v[38:41], v[142:145], v[192:195], 0
	v_mfma_f32_16x16x32_bf16 v[34:37], v[150:153], v[192:195], 0
	v_mfma_f32_16x16x32_bf16 v[22:25], v[142:145], v[200:203], 0
	v_mfma_f32_16x16x32_bf16 v[18:21], v[150:153], v[200:203], 0
	v_mfma_f32_16x16x32_bf16 v[62:65], v[146:149], v[178:181], v[62:65]
	v_mfma_f32_16x16x32_bf16 v[58:61], v[154:157], v[178:181], v[58:61]
	v_mfma_f32_16x16x32_bf16 v[54:57], v[146:149], v[186:189], v[54:57]
	v_mfma_f32_16x16x32_bf16 v[50:53], v[154:157], v[186:189], v[50:53]
	v_mfma_f32_16x16x32_bf16 v[38:41], v[146:149], v[196:199], v[38:41]
	v_mfma_f32_16x16x32_bf16 v[34:37], v[154:157], v[196:199], v[34:37]
	v_mfma_f32_16x16x32_bf16 v[22:25], v[146:149], v[204:207], v[22:25]
	v_mfma_f32_16x16x32_bf16 v[18:21], v[154:157], v[204:207], v[18:21]
	s_setprio 0
	s_setprio 1
	v_mfma_f32_16x16x32_bf16 v[46:49], v[158:161], v[174:177], 0
	v_mfma_f32_16x16x32_bf16 v[42:45], v[166:169], v[174:177], 0
	v_mfma_f32_16x16x32_bf16 v[30:33], v[158:161], v[182:185], 0
	v_mfma_f32_16x16x32_bf16 v[26:29], v[166:169], v[182:185], 0
	v_mfma_f32_16x16x32_bf16 v[14:17], v[158:161], v[192:195], 0
	v_mfma_f32_16x16x32_bf16 v[10:13], v[166:169], v[192:195], 0
	v_mfma_f32_16x16x32_bf16 v[6:9], v[158:161], v[200:203], 0
	v_mfma_f32_16x16x32_bf16 v[2:5], v[166:169], v[200:203], 0
	v_mfma_f32_16x16x32_bf16 v[46:49], v[162:165], v[178:181], v[46:49]
	v_mfma_f32_16x16x32_bf16 v[42:45], v[170:173], v[178:181], v[42:45]
	v_mfma_f32_16x16x32_bf16 v[30:33], v[162:165], v[186:189], v[30:33]
	v_mfma_f32_16x16x32_bf16 v[26:29], v[170:173], v[186:189], v[26:29]
	v_mfma_f32_16x16x32_bf16 v[14:17], v[162:165], v[196:199], v[14:17]
	v_mfma_f32_16x16x32_bf16 v[10:13], v[170:173], v[196:199], v[10:13]
	v_mfma_f32_16x16x32_bf16 v[6:9], v[162:165], v[204:207], v[6:9]
	v_mfma_f32_16x16x32_bf16 v[2:5], v[170:173], v[204:207], v[2:5]
	s_setprio 0
	s_barrier
	s_add_i32 s85, 0, 0x18000
	s_add_i32 s93, 0, 0x1c000
	v_add_u32_e32 v154, s85, v140
	v_add_u32_e32 v170, s93, v140
	ds_read_b128 v[142:145], v154
	ds_read_b128 v[146:149], v154 offset:1024
	ds_read_b128 v[150:153], v154 offset:2048
	ds_read_b128 v[154:157], v154 offset:3072
	ds_read_b128 v[158:161], v170
	ds_read_b128 v[162:165], v170 offset:1024
	ds_read_b128 v[166:169], v170 offset:2048
	ds_read_b128 v[170:173], v170 offset:3072
	s_add_u32 s58, s58, 0x40000
	s_addc_u32 s59, s59, 0
	s_mov_b32 m0, s57
	v_lshl_add_u64 v[216:217], s[58:59], 0, v[130:131]
	ds_read_b128 v[174:177], v141 offset:32768
	ds_read_b128 v[178:181], v141 offset:33792
	ds_read_b128 v[182:185], v141 offset:34816
	ds_read_b128 v[186:189], v141 offset:35840
	ds_read_b128 v[192:195], v141 offset:36864
	ds_read_b128 v[196:199], v141 offset:37888
	ds_read_b128 v[200:203], v141 offset:38912
	ds_read_b128 v[204:207], v141 offset:39936
	global_load_lds_dwordx4 v[216:217], off
	v_lshl_add_u64 v[216:217], s[58:59], 0, v[132:133]
	s_mov_b32 m0, s66
	s_nop 0
	global_load_lds_dwordx4 v[216:217], off
	s_waitcnt vmcnt(8)
	s_waitcnt lgkmcnt(0)
	s_barrier
	s_setprio 1
	s_waitcnt lgkmcnt(0)
	v_mfma_f32_16x16x32_bf16 v[126:129], v[142:145], v[174:177], v[126:129]
	v_mfma_f32_16x16x32_bf16 v[122:125], v[150:153], v[174:177], v[122:125]
	v_mfma_f32_16x16x32_bf16 v[118:121], v[142:145], v[182:185], v[118:121]
	v_mfma_f32_16x16x32_bf16 v[114:117], v[150:153], v[182:185], v[114:117]
	v_mfma_f32_16x16x32_bf16 v[102:105], v[142:145], v[192:195], v[102:105]
	v_mfma_f32_16x16x32_bf16 v[98:101], v[150:153], v[192:195], v[98:101]
	v_mfma_f32_16x16x32_bf16 v[86:89], v[142:145], v[200:203], v[86:89]
	v_mfma_f32_16x16x32_bf16 v[82:85], v[150:153], v[200:203], v[82:85]
	v_mfma_f32_16x16x32_bf16 v[126:129], v[146:149], v[178:181], v[126:129]
	v_mfma_f32_16x16x32_bf16 v[122:125], v[154:157], v[178:181], v[122:125]
	v_mfma_f32_16x16x32_bf16 v[118:121], v[146:149], v[186:189], v[118:121]
	v_mfma_f32_16x16x32_bf16 v[114:117], v[154:157], v[186:189], v[114:117]
	v_mfma_f32_16x16x32_bf16 v[102:105], v[146:149], v[196:199], v[102:105]
	v_mfma_f32_16x16x32_bf16 v[98:101], v[154:157], v[196:199], v[98:101]
	v_mfma_f32_16x16x32_bf16 v[86:89], v[146:149], v[204:207], v[86:89]
	v_mfma_f32_16x16x32_bf16 v[82:85], v[154:157], v[204:207], v[82:85]
	s_setprio 0
	s_setprio 1
	v_mfma_f32_16x16x32_bf16 v[110:113], v[158:161], v[174:177], v[110:113]
	v_mfma_f32_16x16x32_bf16 v[106:109], v[166:169], v[174:177], v[106:109]
	v_mfma_f32_16x16x32_bf16 v[94:97], v[158:161], v[182:185], v[94:97]
	v_mfma_f32_16x16x32_bf16 v[90:93], v[166:169], v[182:185], v[90:93]
	v_mfma_f32_16x16x32_bf16 v[78:81], v[158:161], v[192:195], v[78:81]
	v_mfma_f32_16x16x32_bf16 v[74:77], v[166:169], v[192:195], v[74:77]
	v_mfma_f32_16x16x32_bf16 v[70:73], v[158:161], v[200:203], v[70:73]
	v_mfma_f32_16x16x32_bf16 v[66:69], v[166:169], v[200:203], v[66:69]
	v_mfma_f32_16x16x32_bf16 v[110:113], v[162:165], v[178:181], v[110:113]
	v_mfma_f32_16x16x32_bf16 v[106:109], v[170:173], v[178:181], v[106:109]
	v_mfma_f32_16x16x32_bf16 v[94:97], v[162:165], v[186:189], v[94:97]
	v_mfma_f32_16x16x32_bf16 v[90:93], v[170:173], v[186:189], v[90:93]
	v_mfma_f32_16x16x32_bf16 v[78:81], v[162:165], v[196:199], v[78:81]
	v_mfma_f32_16x16x32_bf16 v[74:77], v[170:173], v[196:199], v[74:77]
	v_mfma_f32_16x16x32_bf16 v[70:73], v[162:165], v[204:207], v[70:73]
	v_mfma_f32_16x16x32_bf16 v[66:69], v[170:173], v[204:207], v[66:69]
	s_setprio 0
	s_barrier
	s_add_i32 s58, s85, s49
	v_lshl_add_u64 v[208:209], v[208:209], 0, s[86:87]
	s_mov_b32 m0, s58
	ds_read_b128 v[174:177], v141 offset:49152
	ds_read_b128 v[178:181], v141 offset:50176
	ds_read_b128 v[182:185], v141 offset:51200
	ds_read_b128 v[186:189], v141 offset:52224
	ds_read_b128 v[192:195], v141 offset:53248
	ds_read_b128 v[196:199], v141 offset:54272
	ds_read_b128 v[200:203], v141 offset:55296
	ds_read_b128 v[204:207], v141 offset:56320
	global_load_lds_dwordx4 v[208:209], off
	s_add_i32 m0, s58, 0x2000
	s_add_u32 s44, s44, 0x40080
	v_lshl_add_u64 v[208:209], v[210:211], 0, s[86:87]
	s_addc_u32 s45, s45, 0
	s_add_i32 s58, s93, s49
	global_load_lds_dwordx4 v[208:209], off
	v_lshl_add_u64 v[208:209], s[44:45], 0, v[0:1]
	s_mov_b32 m0, s58
	s_nop 0
	global_load_lds_dwordx4 v[208:209], off
	v_lshl_add_u64 v[208:209], s[44:45], 0, v[134:135]
	s_add_i32 m0, s58, 0x2000
	s_nop 0
	global_load_lds_dwordx4 v[208:209], off
	v_lshl_add_u64 v[208:209], v[212:213], 0, s[86:87]
	s_mov_b32 m0, s71
	s_nop 0
	global_load_lds_dwordx4 v[208:209], off
	v_lshl_add_u64 v[208:209], v[214:215], 0, s[86:87]
	s_mov_b32 m0, s74
	s_nop 0
	global_load_lds_dwordx4 v[208:209], off
	s_waitcnt vmcnt(8)
	s_waitcnt lgkmcnt(0)
	s_barrier
	s_setprio 1
	s_waitcnt lgkmcnt(0)
	v_mfma_f32_16x16x32_bf16 v[62:65], v[142:145], v[174:177], v[62:65]
	v_mfma_f32_16x16x32_bf16 v[58:61], v[150:153], v[174:177], v[58:61]
	v_mfma_f32_16x16x32_bf16 v[54:57], v[142:145], v[182:185], v[54:57]
	v_mfma_f32_16x16x32_bf16 v[50:53], v[150:153], v[182:185], v[50:53]
	v_mfma_f32_16x16x32_bf16 v[38:41], v[142:145], v[192:195], v[38:41]
	v_mfma_f32_16x16x32_bf16 v[34:37], v[150:153], v[192:195], v[34:37]
	v_mfma_f32_16x16x32_bf16 v[22:25], v[142:145], v[200:203], v[22:25]
	v_mfma_f32_16x16x32_bf16 v[18:21], v[150:153], v[200:203], v[18:21]
	v_mfma_f32_16x16x32_bf16 v[62:65], v[146:149], v[178:181], v[62:65]
	v_mfma_f32_16x16x32_bf16 v[58:61], v[154:157], v[178:181], v[58:61]
	v_mfma_f32_16x16x32_bf16 v[54:57], v[146:149], v[186:189], v[54:57]
	v_mfma_f32_16x16x32_bf16 v[50:53], v[154:157], v[186:189], v[50:53]
	v_mfma_f32_16x16x32_bf16 v[38:41], v[146:149], v[196:199], v[38:41]
	v_mfma_f32_16x16x32_bf16 v[34:37], v[154:157], v[196:199], v[34:37]
	v_mfma_f32_16x16x32_bf16 v[22:25], v[146:149], v[204:207], v[22:25]
	v_mfma_f32_16x16x32_bf16 v[18:21], v[154:157], v[204:207], v[18:21]
	s_setprio 0
	s_setprio 1
	v_mfma_f32_16x16x32_bf16 v[46:49], v[158:161], v[174:177], v[46:49]
	v_mfma_f32_16x16x32_bf16 v[42:45], v[166:169], v[174:177], v[42:45]
	v_mfma_f32_16x16x32_bf16 v[30:33], v[158:161], v[182:185], v[30:33]
	v_mfma_f32_16x16x32_bf16 v[26:29], v[166:169], v[182:185], v[26:29]
	v_mfma_f32_16x16x32_bf16 v[14:17], v[158:161], v[192:195], v[14:17]
	v_mfma_f32_16x16x32_bf16 v[10:13], v[166:169], v[192:195], v[10:13]
	v_mfma_f32_16x16x32_bf16 v[6:9], v[158:161], v[200:203], v[6:9]
	v_mfma_f32_16x16x32_bf16 v[2:5], v[166:169], v[200:203], v[2:5]
	v_mfma_f32_16x16x32_bf16 v[46:49], v[162:165], v[178:181], v[46:49]
	v_mfma_f32_16x16x32_bf16 v[42:45], v[170:173], v[178:181], v[42:45]
	v_mfma_f32_16x16x32_bf16 v[30:33], v[162:165], v[186:189], v[30:33]
	v_mfma_f32_16x16x32_bf16 v[26:29], v[170:173], v[186:189], v[26:29]
	v_mfma_f32_16x16x32_bf16 v[14:17], v[162:165], v[196:199], v[14:17]
	v_mfma_f32_16x16x32_bf16 v[10:13], v[170:173], v[196:199], v[10:13]
	v_mfma_f32_16x16x32_bf16 v[6:9], v[162:165], v[204:207], v[6:9]
	v_mfma_f32_16x16x32_bf16 v[2:5], v[170:173], v[204:207], v[2:5]
	s_setprio 0
	s_barrier
	s_add_i32 s81, s81, 2
	s_add_u32 s38, s38, 0x100
	s_addc_u32 s39, s39, 0
	s_cmp_lt_u32 s81, 14

.LBB0_234:
	s_ashr_i32 s23, s22, 31
	s_lshl_b64 s[24:25], s[22:23], 19
	s_add_u32 s24, s3, s24
	s_addc_u32 s25, s4, s25
	s_and_b64 s[26:27], s[8:9], exec
	s_cselect_b32 s23, s25, s29
	s_cselect_b32 s77, s24, s28
	s_ashr_i32 s21, s20, 31
	s_lshl_b64 s[26:27], s[20:21], 19
	s_add_u32 s26, s5, s26
	s_addc_u32 s27, s30, s27
	s_and_b64 s[44:45], s[8:9], exec
	s_cselect_b32 s21, s27, s39
	s_cselect_b32 s78, s26, s38
	s_add_u32 s79, s38, 0x100
	s_addc_u32 s81, s39, 0
	s_mov_b32 s85, -2
	s_waitcnt vmcnt(0)
	s_add_u32 s38, s28, 0x100
	s_addc_u32 s39, s29, 0
	s_add_i32 s93, 0, 0x10000
	s_cmp_eq_u32 s85, 12
	s_cselect_b32 s59, s23, s39
	s_cselect_b32 s58, s77, s38
	s_cselect_b32 s45, s21, s81
	s_cselect_b32 s44, s78, s79
	s_add_i32 vcc_lo, 0, 0x14000
	v_add_u32_e32 v142, s93, v158
	v_add_u32_e32 v156, vcc_lo, v158
	ds_read_b128 v[130:133], v142
	ds_read_b128 v[134:137], v142 offset:1024
	ds_read_b128 v[138:141], v142 offset:2048
	ds_read_b128 v[142:145], v142 offset:3072
	ds_read_b128 v[152:155], v156
	ds_read_b128 v[160:163], v156 offset:1024
	ds_read_b128 v[164:167], v156 offset:2048
	ds_read_b128 v[168:171], v156 offset:3072
	v_lshl_add_u64 v[156:157], s[28:29], 0, v[148:149]
	s_add_i32 m0, s42, 0xc000
	ds_read_b128 v[172:175], v159
	ds_read_b128 v[176:179], v159 offset:1024
	ds_read_b128 v[180:183], v159 offset:2048
	ds_read_b128 v[184:187], v159 offset:3072
	ds_read_b128 v[196:199], v159 offset:4096
	ds_read_b128 v[200:203], v159 offset:5120
	ds_read_b128 v[204:207], v159 offset:6144
	ds_read_b128 v[208:211], v159 offset:7168
	global_load_lds_dwordx4 v[156:157], off
	v_lshl_add_u64 v[156:157], s[28:29], 0, v[150:151]
	s_add_i32 m0, s42, 0xe000
	s_nop 0
	global_load_lds_dwordx4 v[156:157], off
	s_waitcnt vmcnt(8)
	s_waitcnt lgkmcnt(0)
	s_barrier
	s_setprio 1
	s_waitcnt lgkmcnt(0)
	v_mfma_f32_16x16x32_bf16 v[126:129], v[130:133], v[172:175], 0
	v_mfma_f32_16x16x32_bf16 v[122:125], v[138:141], v[172:175], 0
	v_mfma_f32_16x16x32_bf16 v[114:117], v[130:133], v[180:183], 0
	v_mfma_f32_16x16x32_bf16 v[110:113], v[138:141], v[180:183], 0
	v_mfma_f32_16x16x32_bf16 v[94:97], v[130:133], v[196:199], 0
	v_mfma_f32_16x16x32_bf16 v[90:93], v[138:141], v[196:199], 0
	v_mfma_f32_16x16x32_bf16 v[86:89], v[130:133], v[204:207], 0
	v_mfma_f32_16x16x32_bf16 v[78:81], v[138:141], v[204:207], 0
	v_mfma_f32_16x16x32_bf16 v[126:129], v[134:137], v[176:179], v[126:129]
	v_mfma_f32_16x16x32_bf16 v[122:125], v[142:145], v[176:179], v[122:125]
	v_mfma_f32_16x16x32_bf16 v[114:117], v[134:137], v[184:187], v[114:117]
	v_mfma_f32_16x16x32_bf16 v[110:113], v[142:145], v[184:187], v[110:113]
	v_mfma_f32_16x16x32_bf16 v[94:97], v[134:137], v[200:203], v[94:97]
	v_mfma_f32_16x16x32_bf16 v[90:93], v[142:145], v[200:203], v[90:93]
	v_mfma_f32_16x16x32_bf16 v[86:89], v[134:137], v[208:211], v[86:89]
	v_mfma_f32_16x16x32_bf16 v[78:81], v[142:145], v[208:211], v[78:81]
	s_setprio 0
	s_setprio 1
	v_mfma_f32_16x16x32_bf16 v[118:121], v[152:155], v[172:175], 0
	v_mfma_f32_16x16x32_bf16 v[106:109], v[164:167], v[172:175], 0
	v_mfma_f32_16x16x32_bf16 v[102:105], v[152:155], v[180:183], 0
	v_mfma_f32_16x16x32_bf16 v[98:101], v[164:167], v[180:183], 0
	v_mfma_f32_16x16x32_bf16 v[82:85], v[152:155], v[196:199], 0
	v_mfma_f32_16x16x32_bf16 v[74:77], v[164:167], v[196:199], 0
	v_mfma_f32_16x16x32_bf16 v[70:73], v[152:155], v[204:207], 0
	v_mfma_f32_16x16x32_bf16 v[66:69], v[164:167], v[204:207], 0
	v_mfma_f32_16x16x32_bf16 v[118:121], v[160:163], v[176:179], v[118:121]
	v_mfma_f32_16x16x32_bf16 v[106:109], v[168:171], v[176:179], v[106:109]
	v_mfma_f32_16x16x32_bf16 v[102:105], v[160:163], v[184:187], v[102:105]
	v_mfma_f32_16x16x32_bf16 v[98:101], v[168:171], v[184:187], v[98:101]
	v_mfma_f32_16x16x32_bf16 v[82:85], v[160:163], v[200:203], v[82:85]
	v_mfma_f32_16x16x32_bf16 v[74:77], v[168:171], v[200:203], v[74:77]
	v_mfma_f32_16x16x32_bf16 v[70:73], v[160:163], v[208:211], v[70:73]
	v_mfma_f32_16x16x32_bf16 v[66:69], v[168:171], v[208:211], v[66:69]
	s_setprio 0
	s_barrier
	s_add_i32 s28, s93, s40
	v_lshl_add_u64 v[156:157], s[44:45], 0, v[0:1]
	s_mov_b32 m0, s28
	ds_read_b128 v[172:175], v159 offset:16384
	ds_read_b128 v[176:179], v159 offset:17408
	ds_read_b128 v[180:183], v159 offset:18432
	ds_read_b128 v[184:187], v159 offset:19456
	ds_read_b128 v[196:199], v159 offset:20480
	ds_read_b128 v[200:203], v159 offset:21504
	ds_read_b128 v[204:207], v159 offset:22528
	ds_read_b128 v[208:211], v159 offset:23552
	global_load_lds_dwordx4 v[156:157], off
	s_add_i32 m0, s28, 0x2000
	s_add_u32 s28, s44, 0x40000
	v_lshl_add_u64 v[188:189], s[44:45], 0, v[146:147]
	s_addc_u32 s29, s45, 0
	s_add_i32 s93, vcc_lo, s40
	global_load_lds_dwordx4 v[188:189], off
	v_lshl_add_u64 v[192:193], s[28:29], 0, v[0:1]
	s_mov_b32 m0, s93
	v_lshl_add_u64 v[194:195], s[58:59], 0, v[146:147]
	global_load_lds_dwordx4 v[192:193], off
	v_lshl_add_u64 v[192:193], s[28:29], 0, v[146:147]
	s_add_i32 m0, s93, 0x2000
	s_nop 0
	global_load_lds_dwordx4 v[192:193], off
	v_lshl_add_u64 v[192:193], s[58:59], 0, v[0:1]
	s_mov_b32 m0, s42
	s_nop 0
	global_load_lds_dwordx4 v[192:193], off
	s_mov_b32 m0, s43
	s_nop 0
	global_load_lds_dwordx4 v[194:195], off
	s_waitcnt vmcnt(8)
	s_waitcnt lgkmcnt(0)
	s_barrier
	s_setprio 1
	s_waitcnt lgkmcnt(0)
	v_mfma_f32_16x16x32_bf16 v[62:65], v[130:133], v[172:175], 0
	v_mfma_f32_16x16x32_bf16 v[58:61], v[138:141], v[172:175], 0
	v_mfma_f32_16x16x32_bf16 v[54:57], v[130:133], v[180:183], 0
	v_mfma_f32_16x16x32_bf16 v[46:49], v[138:141], v[180:183], 0
	v_mfma_f32_16x16x32_bf16 v[34:37], v[130:133], v[196:199], 0
	v_mfma_f32_16x16x32_bf16 v[26:29], v[138:141], v[196:199], 0
	v_mfma_f32_16x16x32_bf16 v[22:25], v[130:133], v[204:207], 0
	v_mfma_f32_16x16x32_bf16 v[14:17], v[138:141], v[204:207], 0
	v_mfma_f32_16x16x32_bf16 v[62:65], v[134:137], v[176:179], v[62:65]
	v_mfma_f32_16x16x32_bf16 v[58:61], v[142:145], v[176:179], v[58:61]
	v_mfma_f32_16x16x32_bf16 v[54:57], v[134:137], v[184:187], v[54:57]
	v_mfma_f32_16x16x32_bf16 v[46:49], v[142:145], v[184:187], v[46:49]
	v_mfma_f32_16x16x32_bf16 v[34:37], v[134:137], v[200:203], v[34:37]
	v_mfma_f32_16x16x32_bf16 v[26:29], v[142:145], v[200:203], v[26:29]
	v_mfma_f32_16x16x32_bf16 v[22:25], v[134:137], v[208:211], v[22:25]
	v_mfma_f32_16x16x32_bf16 v[14:17], v[142:145], v[208:211], v[14:17]
	s_setprio 0
	s_setprio 1
	v_mfma_f32_16x16x32_bf16 v[50:53], v[152:155], v[172:175], 0
	v_mfma_f32_16x16x32_bf16 v[42:45], v[164:167], v[172:175], 0
	v_mfma_f32_16x16x32_bf16 v[38:41], v[152:155], v[180:183], 0
	v_mfma_f32_16x16x32_bf16 v[30:33], v[164:167], v[180:183], 0
	v_mfma_f32_16x16x32_bf16 v[18:21], v[152:155], v[196:199], 0
	v_mfma_f32_16x16x32_bf16 v[10:13], v[164:167], v[196:199], 0
	v_mfma_f32_16x16x32_bf16 v[6:9], v[152:155], v[204:207], 0
	v_mfma_f32_16x16x32_bf16 v[2:5], v[164:167], v[204:207], 0
	v_mfma_f32_16x16x32_bf16 v[50:53], v[160:163], v[176:179], v[50:53]
	v_mfma_f32_16x16x32_bf16 v[42:45], v[168:171], v[176:179], v[42:45]
	v_mfma_f32_16x16x32_bf16 v[38:41], v[160:163], v[184:187], v[38:41]
	v_mfma_f32_16x16x32_bf16 v[30:33], v[168:171], v[184:187], v[30:33]
	v_mfma_f32_16x16x32_bf16 v[18:21], v[160:163], v[200:203], v[18:21]
	v_mfma_f32_16x16x32_bf16 v[10:13], v[168:171], v[200:203], v[10:13]
	v_mfma_f32_16x16x32_bf16 v[6:9], v[160:163], v[208:211], v[6:9]
	v_mfma_f32_16x16x32_bf16 v[2:5], v[168:171], v[208:211], v[2:5]
	s_setprio 0
	s_barrier
	s_add_i32 s93, 0, 0x18000
	s_add_i32 vcc_lo, 0, 0x1c000
	v_add_u32_e32 v142, s93, v158
	v_add_u32_e32 v168, vcc_lo, v158
	ds_read_b128 v[130:133], v142
	ds_read_b128 v[134:137], v142 offset:1024
	ds_read_b128 v[138:141], v142 offset:2048
	ds_read_b128 v[142:145], v142 offset:3072
	ds_read_b128 v[152:155], v168
	ds_read_b128 v[160:163], v168 offset:1024
	ds_read_b128 v[164:167], v168 offset:2048
	ds_read_b128 v[168:171], v168 offset:3072
	s_add_u32 s28, s58, 0x40000
	s_addc_u32 s29, s59, 0
	s_mov_b32 m0, s46
	v_lshl_add_u64 v[212:213], s[28:29], 0, v[0:1]
	ds_read_b128 v[172:175], v159 offset:32768
	ds_read_b128 v[176:179], v159 offset:33792
	ds_read_b128 v[180:183], v159 offset:34816
	ds_read_b128 v[184:187], v159 offset:35840
	ds_read_b128 v[196:199], v159 offset:36864
	ds_read_b128 v[200:203], v159 offset:37888
	ds_read_b128 v[204:207], v159 offset:38912
	ds_read_b128 v[208:211], v159 offset:39936
	global_load_lds_dwordx4 v[212:213], off
	v_lshl_add_u64 v[212:213], s[28:29], 0, v[146:147]
	s_mov_b32 m0, s48
	s_nop 0
	global_load_lds_dwordx4 v[212:213], off
	s_waitcnt vmcnt(8)
	s_waitcnt lgkmcnt(0)
	s_barrier
	s_setprio 1
	s_waitcnt lgkmcnt(0)
	v_mfma_f32_16x16x32_bf16 v[126:129], v[130:133], v[172:175], v[126:129]
	v_mfma_f32_16x16x32_bf16 v[122:125], v[138:141], v[172:175], v[122:125]
	v_mfma_f32_16x16x32_bf16 v[114:117], v[130:133], v[180:183], v[114:117]
	v_mfma_f32_16x16x32_bf16 v[110:113], v[138:141], v[180:183], v[110:113]
	v_mfma_f32_16x16x32_bf16 v[94:97], v[130:133], v[196:199], v[94:97]
	v_mfma_f32_16x16x32_bf16 v[90:93], v[138:141], v[196:199], v[90:93]
	v_mfma_f32_16x16x32_bf16 v[86:89], v[130:133], v[204:207], v[86:89]
	v_mfma_f32_16x16x32_bf16 v[78:81], v[138:141], v[204:207], v[78:81]
	v_mfma_f32_16x16x32_bf16 v[126:129], v[134:137], v[176:179], v[126:129]
	v_mfma_f32_16x16x32_bf16 v[122:125], v[142:145], v[176:179], v[122:125]
	v_mfma_f32_16x16x32_bf16 v[114:117], v[134:137], v[184:187], v[114:117]
	v_mfma_f32_16x16x32_bf16 v[110:113], v[142:145], v[184:187], v[110:113]
	v_mfma_f32_16x16x32_bf16 v[94:97], v[134:137], v[200:203], v[94:97]
	v_mfma_f32_16x16x32_bf16 v[90:93], v[142:145], v[200:203], v[90:93]
	v_mfma_f32_16x16x32_bf16 v[86:89], v[134:137], v[208:211], v[86:89]
	v_mfma_f32_16x16x32_bf16 v[78:81], v[142:145], v[208:211], v[78:81]
	s_setprio 0
	s_setprio 1
	v_mfma_f32_16x16x32_bf16 v[118:121], v[152:155], v[172:175], v[118:121]
	v_mfma_f32_16x16x32_bf16 v[106:109], v[164:167], v[172:175], v[106:109]
	v_mfma_f32_16x16x32_bf16 v[102:105], v[152:155], v[180:183], v[102:105]
	v_mfma_f32_16x16x32_bf16 v[98:101], v[164:167], v[180:183], v[98:101]
	v_mfma_f32_16x16x32_bf16 v[82:85], v[152:155], v[196:199], v[82:85]
	v_mfma_f32_16x16x32_bf16 v[74:77], v[164:167], v[196:199], v[74:77]
	v_mfma_f32_16x16x32_bf16 v[70:73], v[152:155], v[204:207], v[70:73]
	v_mfma_f32_16x16x32_bf16 v[66:69], v[164:167], v[204:207], v[66:69]
	v_mfma_f32_16x16x32_bf16 v[118:121], v[160:163], v[176:179], v[118:121]
	v_mfma_f32_16x16x32_bf16 v[106:109], v[168:171], v[176:179], v[106:109]
	v_mfma_f32_16x16x32_bf16 v[102:105], v[160:163], v[184:187], v[102:105]
	v_mfma_f32_16x16x32_bf16 v[98:101], v[168:171], v[184:187], v[98:101]
	v_mfma_f32_16x16x32_bf16 v[82:85], v[160:163], v[200:203], v[82:85]
	v_mfma_f32_16x16x32_bf16 v[74:77], v[168:171], v[200:203], v[74:77]
	v_mfma_f32_16x16x32_bf16 v[70:73], v[160:163], v[208:211], v[70:73]
	v_mfma_f32_16x16x32_bf16 v[66:69], v[168:171], v[208:211], v[66:69]
	s_setprio 0
	s_barrier
	s_add_i32 s28, s93, s40
	v_lshl_add_u64 v[156:157], v[156:157], 0, s[86:87]
	s_mov_b32 m0, s28
	ds_read_b128 v[172:175], v159 offset:49152
	ds_read_b128 v[176:179], v159 offset:50176
	ds_read_b128 v[180:183], v159 offset:51200
	ds_read_b128 v[184:187], v159 offset:52224
	ds_read_b128 v[196:199], v159 offset:53248
	ds_read_b128 v[200:203], v159 offset:54272
	ds_read_b128 v[204:207], v159 offset:55296
	ds_read_b128 v[208:211], v159 offset:56320
	global_load_lds_dwordx4 v[156:157], off
	s_add_i32 m0, s28, 0x2000
	s_add_u32 s28, s44, 0x40080
	v_lshl_add_u64 v[156:157], v[188:189], 0, s[86:87]
	s_addc_u32 s29, s45, 0
	s_add_i32 s44, vcc_lo, s40
	global_load_lds_dwordx4 v[156:157], off
	v_lshl_add_u64 v[156:157], s[28:29], 0, v[0:1]
	s_mov_b32 m0, s44
	s_nop 0
	global_load_lds_dwordx4 v[156:157], off
	v_lshl_add_u64 v[156:157], s[28:29], 0, v[146:147]
	s_add_i32 m0, s44, 0x2000
	s_nop 0
	global_load_lds_dwordx4 v[156:157], off
	v_lshl_add_u64 v[156:157], v[192:193], 0, s[86:87]
	s_mov_b32 m0, s67
	s_nop 0
	global_load_lds_dwordx4 v[156:157], off
	v_lshl_add_u64 v[156:157], v[194:195], 0, s[86:87]
	s_mov_b32 m0, s70
	s_nop 0
	global_load_lds_dwordx4 v[156:157], off
	s_waitcnt vmcnt(8)
	s_waitcnt lgkmcnt(0)
	s_barrier
	s_setprio 1
	s_waitcnt lgkmcnt(0)
	v_mfma_f32_16x16x32_bf16 v[62:65], v[130:133], v[172:175], v[62:65]
	v_mfma_f32_16x16x32_bf16 v[58:61], v[138:141], v[172:175], v[58:61]
	v_mfma_f32_16x16x32_bf16 v[54:57], v[130:133], v[180:183], v[54:57]
	v_mfma_f32_16x16x32_bf16 v[46:49], v[138:141], v[180:183], v[46:49]
	v_mfma_f32_16x16x32_bf16 v[34:37], v[130:133], v[196:199], v[34:37]
	v_mfma_f32_16x16x32_bf16 v[26:29], v[138:141], v[196:199], v[26:29]
	v_mfma_f32_16x16x32_bf16 v[22:25], v[130:133], v[204:207], v[22:25]
	v_mfma_f32_16x16x32_bf16 v[14:17], v[138:141], v[204:207], v[14:17]
	v_mfma_f32_16x16x32_bf16 v[62:65], v[134:137], v[176:179], v[62:65]
	v_mfma_f32_16x16x32_bf16 v[58:61], v[142:145], v[176:179], v[58:61]
	v_mfma_f32_16x16x32_bf16 v[54:57], v[134:137], v[184:187], v[54:57]
	v_mfma_f32_16x16x32_bf16 v[46:49], v[142:145], v[184:187], v[46:49]
	v_mfma_f32_16x16x32_bf16 v[34:37], v[134:137], v[200:203], v[34:37]
	v_mfma_f32_16x16x32_bf16 v[26:29], v[142:145], v[200:203], v[26:29]
	v_mfma_f32_16x16x32_bf16 v[22:25], v[134:137], v[208:211], v[22:25]
	v_mfma_f32_16x16x32_bf16 v[14:17], v[142:145], v[208:211], v[14:17]
	s_setprio 0
	s_setprio 1
	v_mfma_f32_16x16x32_bf16 v[50:53], v[152:155], v[172:175], v[50:53]
	v_mfma_f32_16x16x32_bf16 v[42:45], v[164:167], v[172:175], v[42:45]
	v_mfma_f32_16x16x32_bf16 v[38:41], v[152:155], v[180:183], v[38:41]
	v_mfma_f32_16x16x32_bf16 v[30:33], v[164:167], v[180:183], v[30:33]
	v_mfma_f32_16x16x32_bf16 v[18:21], v[152:155], v[196:199], v[18:21]
	v_mfma_f32_16x16x32_bf16 v[10:13], v[164:167], v[196:199], v[10:13]
	v_mfma_f32_16x16x32_bf16 v[6:9], v[152:155], v[204:207], v[6:9]
	v_mfma_f32_16x16x32_bf16 v[2:5], v[164:167], v[204:207], v[2:5]
	v_mfma_f32_16x16x32_bf16 v[50:53], v[160:163], v[176:179], v[50:53]
	v_mfma_f32_16x16x32_bf16 v[42:45], v[168:171], v[176:179], v[42:45]
	v_mfma_f32_16x16x32_bf16 v[38:41], v[160:163], v[184:187], v[38:41]
	v_mfma_f32_16x16x32_bf16 v[30:33], v[168:171], v[184:187], v[30:33]
	v_mfma_f32_16x16x32_bf16 v[18:21], v[160:163], v[200:203], v[18:21]
	v_mfma_f32_16x16x32_bf16 v[10:13], v[168:171], v[200:203], v[10:13]
	v_mfma_f32_16x16x32_bf16 v[6:9], v[160:163], v[208:211], v[6:9]
	v_mfma_f32_16x16x32_bf16 v[2:5], v[168:171], v[208:211], v[2:5]
	s_setprio 0
	s_barrier
	s_add_i32 s85, s85, 2
	s_add_u32 s79, s79, 0x100
	s_addc_u32 s81, s81, 0
	s_cmp_gt_u32 s85, 13
	s_mov_b64 s[28:29], s[38:39]

.LBB0_458:
	s_ashr_i32 s29, s28, 31
	s_lshl_b64 s[14:15], s[28:29], 19
	v_readlane_b32 s3, v255, 54
	s_add_u32 s38, s3, s14
	v_readlane_b32 s3, v255, 55
	s_addc_u32 s39, s3, s15
	s_and_b64 s[14:15], s[6:7], exec
	s_cselect_b32 s3, s39, s11
	s_cselect_b32 s9, s38, s10
	s_ashr_i32 s27, s26, 31
	s_lshl_b64 s[14:15], s[26:27], 19
	v_readlane_b32 s13, v255, 50
	s_add_u32 s70, s13, s14
	v_readlane_b32 s13, v255, 51
	s_addc_u32 s71, s13, s15
	s_and_b64 s[14:15], s[6:7], exec
	s_cselect_b32 s13, s71, s59
	s_cselect_b32 s14, s70, s58
	s_add_u32 s10, s10, 0x40080
	s_addc_u32 s11, s11, 0
	s_add_u32 s15, s58, 0x100
	s_addc_u32 s27, s59, 0
	s_mov_b32 s29, -2
	s_waitcnt vmcnt(0)
	s_add_u32 s33, s10, 0xfffc0080
	s_addc_u32 s40, s11, -1
	s_add_i32 s43, 0, 0x10000
	s_cmp_eq_u32 s29, 12
	s_cselect_b32 s67, s3, s40
	s_cselect_b32 s66, s9, s33
	v_add_u32_e32 v0, s43, v245
	s_cselect_b32 s59, s13, s27
	s_cselect_b32 s58, s14, s15
	s_add_i32 s33, 0, 0x14000
	ds_read_b128 v[130:133], v0
	ds_read_b128 v[134:137], v0 offset:1024
	ds_read_b128 v[138:141], v0 offset:2048
	ds_read_b128 v[142:145], v0 offset:3072
	v_add_u32_e32 v0, s33, v245
	ds_read_b128 v[146:149], v0
	ds_read_b128 v[150:153], v0 offset:1024
	ds_read_b128 v[154:157], v0 offset:2048
	ds_read_b128 v[158:161], v0 offset:3072
	v_lshl_add_u64 v[192:193], s[10:11], 0, v[200:201]
	s_add_i32 m0, s31, 0xc000
	ds_read_b128 v[162:165], v246
	ds_read_b128 v[166:169], v246 offset:1024
	ds_read_b128 v[170:173], v246 offset:2048
	ds_read_b128 v[174:177], v246 offset:3072
	ds_read_b128 v[178:181], v246 offset:4096
	ds_read_b128 v[182:185], v246 offset:5120
	ds_read_b128 v[204:207], v246 offset:6144
	ds_read_b128 v[208:211], v246 offset:7168
	global_load_lds_dwordx4 v[192:193], off
	v_lshl_add_u64 v[192:193], s[10:11], 0, v[202:203]
	s_add_i32 m0, s31, 0xe000
	s_nop 0
	global_load_lds_dwordx4 v[192:193], off
	s_waitcnt vmcnt(8)
	s_waitcnt lgkmcnt(0)
	s_barrier
	s_setprio 1
	s_waitcnt lgkmcnt(0)
	v_mfma_f32_16x16x32_bf16 v[126:129], v[130:133], v[162:165], 0
	v_mfma_f32_16x16x32_bf16 v[122:125], v[138:141], v[162:165], 0
	v_mfma_f32_16x16x32_bf16 v[110:113], v[130:133], v[170:173], 0
	v_mfma_f32_16x16x32_bf16 v[106:109], v[138:141], v[170:173], 0
	v_mfma_f32_16x16x32_bf16 v[94:97], v[130:133], v[178:181], 0
	v_mfma_f32_16x16x32_bf16 v[90:93], v[138:141], v[178:181], 0
	v_mfma_f32_16x16x32_bf16 v[78:81], v[130:133], v[204:207], 0
	v_mfma_f32_16x16x32_bf16 v[74:77], v[138:141], v[204:207], 0
	v_mfma_f32_16x16x32_bf16 v[126:129], v[134:137], v[166:169], v[126:129]
	v_mfma_f32_16x16x32_bf16 v[122:125], v[142:145], v[166:169], v[122:125]
	v_mfma_f32_16x16x32_bf16 v[110:113], v[134:137], v[174:177], v[110:113]
	v_mfma_f32_16x16x32_bf16 v[106:109], v[142:145], v[174:177], v[106:109]
	v_mfma_f32_16x16x32_bf16 v[94:97], v[134:137], v[182:185], v[94:97]
	v_mfma_f32_16x16x32_bf16 v[90:93], v[142:145], v[182:185], v[90:93]
	v_mfma_f32_16x16x32_bf16 v[78:81], v[134:137], v[208:211], v[78:81]
	v_mfma_f32_16x16x32_bf16 v[74:77], v[142:145], v[208:211], v[74:77]
	s_setprio 0
	s_setprio 1
	v_mfma_f32_16x16x32_bf16 v[118:121], v[146:149], v[162:165], 0
	v_mfma_f32_16x16x32_bf16 v[114:117], v[154:157], v[162:165], 0
	v_mfma_f32_16x16x32_bf16 v[102:105], v[146:149], v[170:173], 0
	v_mfma_f32_16x16x32_bf16 v[98:101], v[154:157], v[170:173], 0
	v_mfma_f32_16x16x32_bf16 v[86:89], v[146:149], v[178:181], 0
	v_mfma_f32_16x16x32_bf16 v[82:85], v[154:157], v[178:181], 0
	v_mfma_f32_16x16x32_bf16 v[70:73], v[146:149], v[204:207], 0
	v_mfma_f32_16x16x32_bf16 v[66:69], v[154:157], v[204:207], 0
	v_mfma_f32_16x16x32_bf16 v[118:121], v[150:153], v[166:169], v[118:121]
	v_mfma_f32_16x16x32_bf16 v[114:117], v[158:161], v[166:169], v[114:117]
	v_mfma_f32_16x16x32_bf16 v[102:105], v[150:153], v[174:177], v[102:105]
	v_mfma_f32_16x16x32_bf16 v[98:101], v[158:161], v[174:177], v[98:101]
	v_mfma_f32_16x16x32_bf16 v[86:89], v[150:153], v[182:185], v[86:89]
	v_mfma_f32_16x16x32_bf16 v[82:85], v[158:161], v[182:185], v[82:85]
	v_mfma_f32_16x16x32_bf16 v[70:73], v[150:153], v[208:211], v[70:73]
	v_mfma_f32_16x16x32_bf16 v[66:69], v[158:161], v[208:211], v[66:69]
	s_setprio 0
	s_barrier
	s_add_i32 s40, s43, s30
	v_lshl_add_u64 v[192:193], s[58:59], 0, v[188:189]
	s_mov_b32 m0, s40
	ds_read_b128 v[162:165], v246 offset:16384
	ds_read_b128 v[166:169], v246 offset:17408
	ds_read_b128 v[170:173], v246 offset:18432
	ds_read_b128 v[174:177], v246 offset:19456
	ds_read_b128 v[178:181], v246 offset:20480
	ds_read_b128 v[182:185], v246 offset:21504
	ds_read_b128 v[204:207], v246 offset:22528
	ds_read_b128 v[208:211], v246 offset:23552
	global_load_lds_dwordx4 v[192:193], off
	s_add_i32 m0, s40, 0x2000
	s_add_u32 s48, s58, 0x40000
	v_lshl_add_u64 v[194:195], s[58:59], 0, v[198:199]
	s_addc_u32 s49, s59, 0
	s_add_i32 s33, s33, s30
	global_load_lds_dwordx4 v[194:195], off
	v_lshl_add_u64 v[212:213], s[48:49], 0, v[188:189]
	s_mov_b32 m0, s33
	v_lshl_add_u64 v[214:215], s[66:67], 0, v[196:197]
	global_load_lds_dwordx4 v[212:213], off
	v_lshl_add_u64 v[212:213], s[48:49], 0, v[198:199]
	s_add_i32 m0, s33, 0x2000
	s_nop 0
	global_load_lds_dwordx4 v[212:213], off
	v_lshl_add_u64 v[212:213], s[66:67], 0, v[186:187]
	s_mov_b32 m0, s31
	s_nop 0
	global_load_lds_dwordx4 v[212:213], off
	s_mov_b32 m0, s37
	s_nop 0
	global_load_lds_dwordx4 v[214:215], off
	s_waitcnt vmcnt(8)
	s_waitcnt lgkmcnt(0)
	s_barrier
	s_setprio 1
	s_waitcnt lgkmcnt(0)
	v_mfma_f32_16x16x32_bf16 v[62:65], v[130:133], v[162:165], 0
	v_mfma_f32_16x16x32_bf16 v[58:61], v[138:141], v[162:165], 0
	v_mfma_f32_16x16x32_bf16 v[46:49], v[130:133], v[170:173], 0
	v_mfma_f32_16x16x32_bf16 v[42:45], v[138:141], v[170:173], 0
	v_mfma_f32_16x16x32_bf16 v[30:33], v[130:133], v[178:181], 0
	v_mfma_f32_16x16x32_bf16 v[26:29], v[138:141], v[178:181], 0
	v_mfma_f32_16x16x32_bf16 v[14:17], v[130:133], v[204:207], 0
	v_mfma_f32_16x16x32_bf16 v[10:13], v[138:141], v[204:207], 0
	v_mfma_f32_16x16x32_bf16 v[62:65], v[134:137], v[166:169], v[62:65]
	v_mfma_f32_16x16x32_bf16 v[58:61], v[142:145], v[166:169], v[58:61]
	v_mfma_f32_16x16x32_bf16 v[46:49], v[134:137], v[174:177], v[46:49]
	v_mfma_f32_16x16x32_bf16 v[42:45], v[142:145], v[174:177], v[42:45]
	v_mfma_f32_16x16x32_bf16 v[30:33], v[134:137], v[182:185], v[30:33]
	v_mfma_f32_16x16x32_bf16 v[26:29], v[142:145], v[182:185], v[26:29]
	v_mfma_f32_16x16x32_bf16 v[14:17], v[134:137], v[208:211], v[14:17]
	v_mfma_f32_16x16x32_bf16 v[10:13], v[142:145], v[208:211], v[10:13]
	s_setprio 0
	s_setprio 1
	v_mfma_f32_16x16x32_bf16 v[54:57], v[146:149], v[162:165], 0
	v_mfma_f32_16x16x32_bf16 v[50:53], v[154:157], v[162:165], 0
	v_mfma_f32_16x16x32_bf16 v[38:41], v[146:149], v[170:173], 0
	v_mfma_f32_16x16x32_bf16 v[34:37], v[154:157], v[170:173], 0
	v_mfma_f32_16x16x32_bf16 v[22:25], v[146:149], v[178:181], 0
	v_mfma_f32_16x16x32_bf16 v[18:21], v[154:157], v[178:181], 0
	v_mfma_f32_16x16x32_bf16 v[6:9], v[146:149], v[204:207], 0
	v_mfma_f32_16x16x32_bf16 v[2:5], v[154:157], v[204:207], 0
	v_mfma_f32_16x16x32_bf16 v[54:57], v[150:153], v[166:169], v[54:57]
	v_mfma_f32_16x16x32_bf16 v[50:53], v[158:161], v[166:169], v[50:53]
	v_mfma_f32_16x16x32_bf16 v[38:41], v[150:153], v[174:177], v[38:41]
	v_mfma_f32_16x16x32_bf16 v[34:37], v[158:161], v[174:177], v[34:37]
	v_mfma_f32_16x16x32_bf16 v[22:25], v[150:153], v[182:185], v[22:25]
	v_mfma_f32_16x16x32_bf16 v[18:21], v[158:161], v[182:185], v[18:21]
	v_mfma_f32_16x16x32_bf16 v[6:9], v[150:153], v[208:211], v[6:9]
	v_mfma_f32_16x16x32_bf16 v[2:5], v[158:161], v[208:211], v[2:5]
	s_setprio 0
	s_barrier
	s_add_i32 s33, 0, 0x18000
	v_add_u32_e32 v0, s33, v245
	s_add_i32 s40, 0, 0x1c000
	ds_read_b128 v[130:133], v0
	ds_read_b128 v[134:137], v0 offset:1024
	ds_read_b128 v[138:141], v0 offset:2048
	ds_read_b128 v[142:145], v0 offset:3072
	v_add_u32_e32 v0, s40, v245
	ds_read_b128 v[146:149], v0
	ds_read_b128 v[150:153], v0 offset:1024
	ds_read_b128 v[154:157], v0 offset:2048
	ds_read_b128 v[158:161], v0 offset:3072
	s_add_u32 s48, s66, 0x40000
	s_addc_u32 s49, s67, 0
	s_mov_b32 m0, s42
	v_lshl_add_u64 v[216:217], s[48:49], 0, v[186:187]
	ds_read_b128 v[162:165], v246 offset:32768
	ds_read_b128 v[166:169], v246 offset:33792
	ds_read_b128 v[170:173], v246 offset:34816
	ds_read_b128 v[174:177], v246 offset:35840
	ds_read_b128 v[178:181], v246 offset:36864
	ds_read_b128 v[182:185], v246 offset:37888
	ds_read_b128 v[204:207], v246 offset:38912
	ds_read_b128 v[208:211], v246 offset:39936
	global_load_lds_dwordx4 v[216:217], off
	v_lshl_add_u64 v[216:217], s[48:49], 0, v[196:197]
	s_mov_b32 m0, s46
	s_nop 0
	global_load_lds_dwordx4 v[216:217], off
	s_waitcnt vmcnt(8)
	s_waitcnt lgkmcnt(0)
	s_barrier
	s_setprio 1
	s_waitcnt lgkmcnt(0)
	v_mfma_f32_16x16x32_bf16 v[126:129], v[130:133], v[162:165], v[126:129]
	v_mfma_f32_16x16x32_bf16 v[122:125], v[138:141], v[162:165], v[122:125]
	v_mfma_f32_16x16x32_bf16 v[110:113], v[130:133], v[170:173], v[110:113]
	v_mfma_f32_16x16x32_bf16 v[106:109], v[138:141], v[170:173], v[106:109]
	v_mfma_f32_16x16x32_bf16 v[94:97], v[130:133], v[178:181], v[94:97]
	v_mfma_f32_16x16x32_bf16 v[90:93], v[138:141], v[178:181], v[90:93]
	v_mfma_f32_16x16x32_bf16 v[78:81], v[130:133], v[204:207], v[78:81]
	v_mfma_f32_16x16x32_bf16 v[74:77], v[138:141], v[204:207], v[74:77]
	v_mfma_f32_16x16x32_bf16 v[126:129], v[134:137], v[166:169], v[126:129]
	v_mfma_f32_16x16x32_bf16 v[122:125], v[142:145], v[166:169], v[122:125]
	v_mfma_f32_16x16x32_bf16 v[110:113], v[134:137], v[174:177], v[110:113]
	v_mfma_f32_16x16x32_bf16 v[106:109], v[142:145], v[174:177], v[106:109]
	v_mfma_f32_16x16x32_bf16 v[94:97], v[134:137], v[182:185], v[94:97]
	v_mfma_f32_16x16x32_bf16 v[90:93], v[142:145], v[182:185], v[90:93]
	v_mfma_f32_16x16x32_bf16 v[78:81], v[134:137], v[208:211], v[78:81]
	v_mfma_f32_16x16x32_bf16 v[74:77], v[142:145], v[208:211], v[74:77]
	s_setprio 0
	s_setprio 1
	v_mfma_f32_16x16x32_bf16 v[118:121], v[146:149], v[162:165], v[118:121]
	v_mfma_f32_16x16x32_bf16 v[114:117], v[154:157], v[162:165], v[114:117]
	v_mfma_f32_16x16x32_bf16 v[102:105], v[146:149], v[170:173], v[102:105]
	v_mfma_f32_16x16x32_bf16 v[98:101], v[154:157], v[170:173], v[98:101]
	v_mfma_f32_16x16x32_bf16 v[86:89], v[146:149], v[178:181], v[86:89]
	v_mfma_f32_16x16x32_bf16 v[82:85], v[154:157], v[178:181], v[82:85]
	v_mfma_f32_16x16x32_bf16 v[70:73], v[146:149], v[204:207], v[70:73]
	v_mfma_f32_16x16x32_bf16 v[66:69], v[154:157], v[204:207], v[66:69]
	v_mfma_f32_16x16x32_bf16 v[118:121], v[150:153], v[166:169], v[118:121]
	v_mfma_f32_16x16x32_bf16 v[114:117], v[158:161], v[166:169], v[114:117]
	v_mfma_f32_16x16x32_bf16 v[102:105], v[150:153], v[174:177], v[102:105]
	v_mfma_f32_16x16x32_bf16 v[98:101], v[158:161], v[174:177], v[98:101]
	v_mfma_f32_16x16x32_bf16 v[86:89], v[150:153], v[182:185], v[86:89]
	v_mfma_f32_16x16x32_bf16 v[82:85], v[158:161], v[182:185], v[82:85]
	v_mfma_f32_16x16x32_bf16 v[70:73], v[150:153], v[208:211], v[70:73]
	v_mfma_f32_16x16x32_bf16 v[66:69], v[158:161], v[208:211], v[66:69]
	s_setprio 0
	s_barrier
	s_add_i32 s33, s33, s30
	v_lshl_add_u64 v[192:193], v[192:193], 0, s[86:87]
	s_mov_b32 m0, s33
	ds_read_b128 v[162:165], v246 offset:49152
	ds_read_b128 v[166:169], v246 offset:50176
	ds_read_b128 v[170:173], v246 offset:51200
	ds_read_b128 v[174:177], v246 offset:52224
	ds_read_b128 v[178:181], v246 offset:53248
	ds_read_b128 v[182:185], v246 offset:54272
	ds_read_b128 v[204:207], v246 offset:55296
	ds_read_b128 v[208:211], v246 offset:56320
	global_load_lds_dwordx4 v[192:193], off
	s_add_i32 m0, s33, 0x2000
	s_add_u32 s48, s58, 0x40080
	v_lshl_add_u64 v[192:193], v[194:195], 0, s[86:87]
	s_addc_u32 s49, s59, 0
	s_add_i32 s33, s40, s30
	global_load_lds_dwordx4 v[192:193], off
	v_lshl_add_u64 v[192:193], s[48:49], 0, v[188:189]
	s_mov_b32 m0, s33
	s_nop 0
	global_load_lds_dwordx4 v[192:193], off
	v_lshl_add_u64 v[192:193], s[48:49], 0, v[198:199]
	s_add_i32 m0, s33, 0x2000
	s_nop 0
	global_load_lds_dwordx4 v[192:193], off
	v_lshl_add_u64 v[192:193], v[212:213], 0, s[86:87]
	s_mov_b32 m0, s74
	s_nop 0
	global_load_lds_dwordx4 v[192:193], off
	v_lshl_add_u64 v[192:193], v[214:215], 0, s[86:87]
	s_mov_b32 m0, s76
	s_nop 0
	global_load_lds_dwordx4 v[192:193], off
	s_waitcnt vmcnt(8)
	s_waitcnt lgkmcnt(0)
	s_barrier
	s_setprio 1
	s_waitcnt lgkmcnt(0)
	v_mfma_f32_16x16x32_bf16 v[62:65], v[130:133], v[162:165], v[62:65]
	v_mfma_f32_16x16x32_bf16 v[58:61], v[138:141], v[162:165], v[58:61]
	v_mfma_f32_16x16x32_bf16 v[46:49], v[130:133], v[170:173], v[46:49]
	v_mfma_f32_16x16x32_bf16 v[42:45], v[138:141], v[170:173], v[42:45]
	v_mfma_f32_16x16x32_bf16 v[30:33], v[130:133], v[178:181], v[30:33]
	v_mfma_f32_16x16x32_bf16 v[26:29], v[138:141], v[178:181], v[26:29]
	v_mfma_f32_16x16x32_bf16 v[14:17], v[130:133], v[204:207], v[14:17]
	v_mfma_f32_16x16x32_bf16 v[10:13], v[138:141], v[204:207], v[10:13]
	v_mfma_f32_16x16x32_bf16 v[62:65], v[134:137], v[166:169], v[62:65]
	v_mfma_f32_16x16x32_bf16 v[58:61], v[142:145], v[166:169], v[58:61]
	v_mfma_f32_16x16x32_bf16 v[46:49], v[134:137], v[174:177], v[46:49]
	v_mfma_f32_16x16x32_bf16 v[42:45], v[142:145], v[174:177], v[42:45]
	v_mfma_f32_16x16x32_bf16 v[30:33], v[134:137], v[182:185], v[30:33]
	v_mfma_f32_16x16x32_bf16 v[26:29], v[142:145], v[182:185], v[26:29]
	v_mfma_f32_16x16x32_bf16 v[14:17], v[134:137], v[208:211], v[14:17]
	v_mfma_f32_16x16x32_bf16 v[10:13], v[142:145], v[208:211], v[10:13]
	s_setprio 0
	s_setprio 1
	v_mfma_f32_16x16x32_bf16 v[54:57], v[146:149], v[162:165], v[54:57]
	v_mfma_f32_16x16x32_bf16 v[50:53], v[154:157], v[162:165], v[50:53]
	v_mfma_f32_16x16x32_bf16 v[38:41], v[146:149], v[170:173], v[38:41]
	v_mfma_f32_16x16x32_bf16 v[34:37], v[154:157], v[170:173], v[34:37]
	v_mfma_f32_16x16x32_bf16 v[22:25], v[146:149], v[178:181], v[22:25]
	v_mfma_f32_16x16x32_bf16 v[18:21], v[154:157], v[178:181], v[18:21]
	v_mfma_f32_16x16x32_bf16 v[6:9], v[146:149], v[204:207], v[6:9]
	v_mfma_f32_16x16x32_bf16 v[2:5], v[154:157], v[204:207], v[2:5]
	v_mfma_f32_16x16x32_bf16 v[54:57], v[150:153], v[166:169], v[54:57]
	v_mfma_f32_16x16x32_bf16 v[50:53], v[158:161], v[166:169], v[50:53]
	v_mfma_f32_16x16x32_bf16 v[38:41], v[150:153], v[174:177], v[38:41]
	v_mfma_f32_16x16x32_bf16 v[34:37], v[158:161], v[174:177], v[34:37]
	v_mfma_f32_16x16x32_bf16 v[22:25], v[150:153], v[182:185], v[22:25]
	v_mfma_f32_16x16x32_bf16 v[18:21], v[158:161], v[182:185], v[18:21]
	v_mfma_f32_16x16x32_bf16 v[6:9], v[150:153], v[208:211], v[6:9]
	v_mfma_f32_16x16x32_bf16 v[2:5], v[158:161], v[208:211], v[2:5]
	s_setprio 0
	s_barrier
	s_add_i32 s29, s29, 2
	s_add_u32 s10, s10, 0x100
	s_addc_u32 s11, s11, 0
	s_add_u32 s15, s15, 0x100
	s_addc_u32 s27, s27, 0
	s_cmp_gt_u32 s29, 13
